# nsa cmp unit: first-tile K fragment reads of pass 1 hoisted into previous head epilogue, pass 2 first-tile reads issued right after the row-sum bpermute
# speedup vs baseline: 1.0030x; 1.0030x over previous
; DI void nsa_cmp_unit(const Params& p, int u, char* smem) {
;     ...
;   const int qb = u & 31, g = (u >> 5) & 1, b = u >> 6;
;   constexpr int VSTR = 264;
;   bf16_t* Kc = (bf16_t*)smem; bf16_t* Vc = (bf16_t*)(smem + 36864);
;   __syncthreads();
;   {
;     const bf16_t* ksrc = p.kcmp + (size_t)(b * 2 + g) * 256 * 64; const bf16_t* vsrc = p.vtcmp + (size_t)(b * 2 + g) * 64 * 256;
; #pragma unroll
;     for (int q = 0; q < 8; ++q) {
;       const int idx = tid + 256 * q;
;       *(u32x4*)(Kc + (idx >> 3) * LSTR + (idx & 7) * 8) = *(const u32x4*)(ksrc + (size_t)idx * 8);
;       *(u32x4*)(Vc + (idx >> 5) * VSTR + (idx & 31) * 8) = *(const u32x4*)(vsrc + (size_t)idx * 8);
;     }
;   }
;   __syncthreads();
;   const int q0 = 128 * qb + 32 * w, tq = q0 + r; const size_t tok = (size_t)b * SEQ + tq;
.LBB0_430:
	s_ashr_i32 s4, s1, 6
	s_bfe_u32 s10, s1, 0x10005
	s_lshl_b32 s2, s4, 1
	s_or_b32 s2, s2, s10
	s_ashr_i32 s3, s2, 31
	v_readlane_b32 s12, v230, 51
	s_lshl_b64 s[2:3], s[2:3], 15
	v_readlane_b32 s26, v229, 1
	s_waitcnt vmcnt(11)
	v_mov_b32_e32 v114, v167
	v_readlane_b32 s27, v229, 2
	s_add_u32 s8, s26, s2
	s_addc_u32 s9, s27, s3
	v_readlane_b32 s6, v229, 19
	v_ashrrev_i32_e32 v115, 31, v114
	v_readlane_b32 s7, v229, 20
	s_add_u32 s6, s6, s2
	v_lshlrev_b64 v[6:7], 4, v[114:115]
	v_add_u32_e32 v66, 0x100, v114
	v_add_u32_e32 v68, 0x200, v114
	s_addc_u32 s7, s7, s3
	v_lshl_add_u64 v[2:3], s[8:9], 0, v[6:7]
	v_ashrrev_i32_e32 v67, 31, v66
	v_ashrrev_i32_e32 v69, 31, v68
	s_barrier
	global_load_dwordx4 v[2:5], v[2:3], off
	v_lshl_add_u64 v[6:7], s[6:7], 0, v[6:7]
	v_lshlrev_b64 v[14:15], 4, v[66:67]
	v_lshlrev_b64 v[22:23], 4, v[68:69]
	global_load_dwordx4 v[6:9], v[6:7], off
	v_lshl_add_u64 v[10:11], s[8:9], 0, v[14:15]
	v_lshl_add_u64 v[18:19], s[8:9], 0, v[22:23]
	global_load_dwordx4 v[10:13], v[10:11], off
	v_lshl_add_u64 v[14:15], s[6:7], 0, v[14:15]
	global_load_dwordx4 v[18:21], v[18:19], off
	v_add_u32_e32 v70, 0x300, v114
	global_load_dwordx4 v[14:17], v[14:15], off
	v_lshl_add_u64 v[22:23], s[6:7], 0, v[22:23]
	v_ashrrev_i32_e32 v71, 31, v70
	global_load_dwordx4 v[22:25], v[22:23], off
	v_lshlrev_b64 v[30:31], 4, v[70:71]
	v_lshl_add_u64 v[26:27], s[8:9], 0, v[30:31]
	global_load_dwordx4 v[26:29], v[26:27], off
	v_add_u32_e32 v72, 0x400, v114
	v_lshl_add_u64 v[30:31], s[6:7], 0, v[30:31]
	v_ashrrev_i32_e32 v73, 31, v72
	global_load_dwordx4 v[30:33], v[30:31], off
	v_lshlrev_b64 v[38:39], 4, v[72:73]
	v_lshl_add_u64 v[34:35], s[8:9], 0, v[38:39]
	global_load_dwordx4 v[34:37], v[34:35], off
	v_add_u32_e32 v74, 0x500, v114
	v_lshl_add_u64 v[38:39], s[6:7], 0, v[38:39]
	v_ashrrev_i32_e32 v75, 31, v74
	global_load_dwordx4 v[38:41], v[38:39], off
	v_lshlrev_b64 v[46:47], 4, v[74:75]
	v_lshl_add_u64 v[42:43], s[8:9], 0, v[46:47]
	global_load_dwordx4 v[42:45], v[42:43], off
	v_add_u32_e32 v76, 0x600, v114
	v_lshl_add_u64 v[46:47], s[6:7], 0, v[46:47]
	v_ashrrev_i32_e32 v77, 31, v76
	global_load_dwordx4 v[46:49], v[46:47], off
	v_lshlrev_b64 v[54:55], 4, v[76:77]
	v_lshl_add_u64 v[50:51], s[8:9], 0, v[54:55]
	global_load_dwordx4 v[50:53], v[50:51], off
	v_add_u32_e32 v78, 0x700, v114
	v_lshl_add_u64 v[54:55], s[6:7], 0, v[54:55]
	v_ashrrev_i32_e32 v79, 31, v78
	global_load_dwordx4 v[54:57], v[54:55], off
	v_lshlrev_b64 v[62:63], 4, v[78:79]
	v_lshl_add_u64 v[58:59], s[8:9], 0, v[62:63]
	global_load_dwordx4 v[58:61], v[58:59], off
	v_lshl_add_u64 v[62:63], s[6:7], 0, v[62:63]
	global_load_dwordx4 v[62:65], v[62:63], off
	v_lshlrev_b32_e32 v0, 4, v114
	v_and_b32_e32 v71, 0x70, v0
	v_lshrrev_b32_e32 v67, 3, v114
	v_and_b32_e32 v73, 0x1f0, v0
	v_add_u32_e32 v0, 0, v71
	s_movk_i32 s8, 0x90
	v_ashrrev_i32_e32 v69, 5, v114
	v_lshrrev_b32_e32 v75, 3, v66
	v_ashrrev_i32_e32 v77, 5, v66
	v_add_u32_e32 v66, 0, v73
	v_mad_u64_u32 v[80:81], s[6:7], v67, s8, v[0:1]
	s_movk_i32 s9, 0x210
	s_waitcnt vmcnt(26)
	v_mad_u64_u32 v[82:83], s[6:7], v69, s9, v[66:67]
	v_mad_u64_u32 v[84:85], s[6:7], v75, s8, v[0:1]
	v_mad_u64_u32 v[86:87], s[6:7], v77, s9, v[66:67]
	s_waitcnt vmcnt(15)
	ds_write_b128 v80, v[2:5]
	s_waitcnt vmcnt(14)
	ds_write_b128 v82, v[6:9] offset:36864
	s_waitcnt vmcnt(13)
	ds_write_b128 v84, v[10:13]
	s_waitcnt vmcnt(11)
	ds_write_b128 v86, v[14:17] offset:36864
	v_lshrrev_b32_e32 v2, 3, v68
	v_mad_u64_u32 v[2:3], s[6:7], v2, s8, v[0:1]
	ds_write_b128 v2, v[18:21]
	v_ashrrev_i32_e32 v2, 5, v68
	v_mad_u64_u32 v[2:3], s[6:7], v2, s9, v[66:67]
	s_waitcnt vmcnt(10)
	ds_write_b128 v2, v[22:25] offset:36864
	v_lshrrev_b32_e32 v2, 3, v70
	v_mad_u64_u32 v[2:3], s[6:7], v2, s8, v[0:1]
	s_waitcnt vmcnt(9)
	ds_write_b128 v2, v[26:29]
	v_ashrrev_i32_e32 v2, 5, v70
	v_mad_u64_u32 v[2:3], s[6:7], v2, s9, v[66:67]
	s_waitcnt vmcnt(8)
	ds_write_b128 v2, v[30:33] offset:36864
	v_lshrrev_b32_e32 v2, 3, v72
	v_mad_u64_u32 v[2:3], s[6:7], v2, s8, v[0:1]
	s_waitcnt vmcnt(7)
	ds_write_b128 v2, v[34:37]
	v_ashrrev_i32_e32 v2, 5, v72
	v_mad_u64_u32 v[2:3], s[6:7], v2, s9, v[66:67]
	s_waitcnt vmcnt(6)
	ds_write_b128 v2, v[38:41] offset:36864
	v_lshrrev_b32_e32 v2, 3, v74
	v_mad_u64_u32 v[2:3], s[6:7], v2, s8, v[0:1]
	s_waitcnt vmcnt(5)
	ds_write_b128 v2, v[42:45]
	v_ashrrev_i32_e32 v2, 5, v74
	v_mad_u64_u32 v[2:3], s[6:7], v2, s9, v[66:67]
	s_waitcnt vmcnt(4)
	ds_write_b128 v2, v[46:49] offset:36864
	v_lshrrev_b32_e32 v2, 3, v76
	v_mad_u64_u32 v[2:3], s[6:7], v2, s8, v[0:1]
	s_waitcnt vmcnt(3)
	ds_write_b128 v2, v[50:53]
	v_ashrrev_i32_e32 v2, 5, v76
	v_mad_u64_u32 v[2:3], s[6:7], v2, s9, v[66:67]
	s_waitcnt vmcnt(2)
	ds_write_b128 v2, v[54:57] offset:36864
	v_lshrrev_b32_e32 v2, 3, v78
	v_mad_u64_u32 v[2:3], s[6:7], v2, s8, v[0:1]
	v_ashrrev_i32_e32 v0, 5, v78
	v_readfirstlane_b32 s5, v114
	s_waitcnt vmcnt(1)
	ds_write_b128 v2, v[58:61]
	v_mad_u64_u32 v[2:3], s[6:7], v0, s9, v[66:67]
	s_lshl_b32 s6, s1, 7
	s_ashr_i32 s29, s5, 1
	s_and_b32 s28, s6, 0xf80
	s_andn2_b32 s29, s29, 31
	v_and_b32_e32 v124, 31, v114
	s_add_i32 s6, s29, s28
	s_waitcnt vmcnt(0)
	ds_write_b128 v2, v[62:65] offset:36864
	v_or_b32_e32 v2, s6, v124
	v_ashrrev_i32_e32 v3, 31, v2
	s_ashr_i32 s5, s4, 31
	v_readlane_b32 s13, v230, 52
	v_readlane_b32 s14, v230, 53
	v_readlane_b32 s15, v230, 54
	v_readlane_b32 s16, v230, 55
	v_readlane_b32 s17, v230, 56
	v_readlane_b32 s18, v230, 57
	v_readlane_b32 s19, v230, 58
	v_readlane_b32 s20, v230, 59
	v_readlane_b32 s21, v230, 60
	v_readlane_b32 s22, v230, 61
	v_readlane_b32 s23, v230, 62
	v_readlane_b32 s24, v230, 63
	v_readlane_b32 s25, v229, 0
	s_lshl_b64 s[4:5], s[4:5], 22
	v_lshlrev_b64 v[4:5], 10, v[2:3]
	v_lshl_add_u64 v[4:5], v[4:5], 0, s[4:5]
	v_readlane_b32 s12, v229, 29
	v_lshlrev_b64 v[4:5], 1, v[4:5]
	v_readlane_b32 s24, v229, 41
	v_readlane_b32 s25, v229, 42
	s_lshl_b32 s58, s10, 10
	v_lshlrev_b32_e32 v0, 1, v166
	v_lshl_add_u64 v[6:7], s[24:25], 0, v[4:5]
	v_lshl_add_u64 v[8:9], v[6:7], 0, s[58:59]
	v_lshl_add_u64 v[8:9], v[8:9], 0, v[0:1]
	s_waitcnt lgkmcnt(0)
	s_barrier
; DI void nsa_cmp_unit(const Params& p, int u, char* smem) {
;     ...
;   const int q0 = 128 * qb + 32 * w, tq = q0 + r; const size_t tok = (size_t)b * SEQ + tq;
;   const int nc = tq >= 31 ? ((tq - 31) >> 4) + 1 : 0;
;   const int ncw = (q0 >> 4) + 1; int ntile = (ncw + 31) >> 5; ntile = ntile > 8 ? 8 : ntile;
;   f32x16 imp[2];
; #pragma unroll
;   for (int jt = 0; jt < 2; ++jt)
; #pragma unroll
;     for (int i = 0; i < 16; ++i) imp[jt][i] = 0.f;
;   bf16x8 qn[4]; load_q(p.Q + tok * 1024 + (8 * g) * 64, qn);
; #pragma unroll 1
;   for (int hd = 0; hd < 8; ++hd) {
;     const int head = 8 * g + hd;
;     bf16x8 qf[4];
; #pragma unroll
;     for (int ks = 0; ks < 4; ++ks) qf[ks] = qn[ks];
;     if (hd + 1 < 8) load_q(p.Q + tok * 1024 + (head + 1) * 64, qn);
	global_load_dwordx4 v[98:101], v[8:9], off offset:32
	global_load_dwordx4 v[102:105], v[8:9], off
	global_load_dwordx4 v[106:109], v[8:9], off offset:64
	global_load_dwordx4 v[110:113], v[8:9], off offset:96
	v_subrev_u32_e32 v3, 31, v2
	v_ashrrev_i32_e32 v3, 4, v3
	v_add_u32_e32 v3, 1, v3
	v_cmp_lt_i32_e32 vcc, 30, v2
	s_ashr_i32 s4, s6, 4
	s_add_i32 s4, s4, 32
	v_cndmask_b32_e32 v116, 0, v3, vcc
	v_and_b32_e32 v3, 64, v202
	v_xor_b32_e32 v2, 32, v202
	v_add_u32_e32 v3, 64, v3
	s_ashr_i32 s4, s4, 5
	v_cmp_lt_i32_e32 vcc, v2, v3
	v_bfe_u32 v8, v114, 5, 1
	s_min_i32 s31, s4, 8
	s_lshl_b32 s54, s10, 3
	v_cndmask_b32_e32 v2, v202, v2, vcc
	s_cmp_gt_i32 s4, 0
	v_lshlrev_b32_e32 v126, 2, v2
	v_lshlrev_b32_e32 v125, 4, v8
	v_mul_u32_u24_e32 v2, 0x210, v124
	v_lshl_add_u64 v[120:121], v[6:7], 0, v[0:1]
	v_mul_u32_u24_e32 v0, 0x90, v124
	s_cselect_b64 s[4:5], -1, 0
	v_add3_u32 v128, v0, v125, 0
	v_lshl_or_b32 v0, v8, 3, v2
	s_add_i32 s6, 0, 0x9000
	v_mov_b32_e32 v14, v1
	v_mov_b32_e32 v15, v1
	v_lshlrev_b32_e32 v127, 2, v8
	v_lshl_add_u64 v[118:119], v[178:179], 0, v[4:5]
	v_add_u32_e32 v130, s6, v0
	v_mov_b32_e32 v0, v1
	v_mov_b32_e32 v2, v1
	v_mov_b32_e32 v3, v1
	v_mov_b32_e32 v4, v1
	v_mov_b32_e32 v5, v1
	v_mov_b32_e32 v6, v1
	v_mov_b32_e32 v7, v1
	v_mov_b32_e32 v8, v1
	v_mov_b32_e32 v9, v1
	v_mov_b32_e32 v10, v1
	v_mov_b32_e32 v11, v1
	v_mov_b32_e32 v12, v1
	v_mov_b32_e32 v13, v1
	v_mov_b64_e32 v[32:33], v[14:15]
	v_lshlrev_b32_e32 v131, 2, v124
	v_mov_b64_e32 v[30:31], v[12:13]
	v_mov_b64_e32 v[28:29], v[10:11]
	v_mov_b64_e32 v[26:27], v[8:9]
	v_mov_b64_e32 v[24:25], v[6:7]
	v_mov_b64_e32 v[22:23], v[4:5]
	v_mov_b64_e32 v[20:21], v[2:3]
	v_mov_b64_e32 v[18:19], v[0:1]
	v_mov_b64_e32 v[16:17], v[14:15]
	s_mov_b32 s30, 0
	v_mov_b32_e32 v115, v116
	v_or_b32_e32 v129, 27, v127
	v_sub_u32_e32 v132, 0, v131
	v_add_u32_e32 v133, -8, v131
	v_add_u32_e32 v134, 0x78, v131
	v_or_b32_e32 v135, 0x80, v131
	v_subrev_u32_e32 v136, 24, v131
	v_add_u32_e32 v137, -16, v131
	v_add_u32_e32 v138, 0x68, v131
	v_add_u32_e32 v139, 0x70, v131
	v_mov_b64_e32 v[14:15], v[12:13]
	v_mov_b64_e32 v[12:13], v[10:11]
	v_mov_b64_e32 v[10:11], v[8:9]
	v_mov_b64_e32 v[8:9], v[6:7]
	v_mov_b64_e32 v[6:7], v[4:5]
	v_mov_b64_e32 v[4:5], v[2:3]
	v_mov_b64_e32 v[2:3], v[0:1]
	v_readlane_b32 s13, v229, 30
	v_readlane_b32 s14, v229, 31
	v_readlane_b32 s15, v229, 32
	v_readlane_b32 s16, v229, 33
	s_waitcnt vmcnt(3)
	v_mov_b64_e32 v[82:83], v[98:99]
	s_waitcnt vmcnt(2)
	v_mov_b64_e32 v[86:87], v[102:103]
	s_waitcnt vmcnt(1)
	v_mov_b64_e32 v[90:91], v[106:107]
	s_waitcnt vmcnt(0)
	v_mov_b64_e32 v[94:95], v[110:111]
	v_mov_b64_e32 v[84:85], v[100:101]
	v_mov_b64_e32 v[88:89], v[104:105]
	v_mov_b64_e32 v[92:93], v[108:109]
	v_mov_b64_e32 v[96:97], v[112:113]
	v_readlane_b32 s17, v229, 34
	v_readlane_b32 s18, v229, 35
	v_readlane_b32 s19, v229, 36
	v_readlane_b32 s20, v229, 37
	v_readlane_b32 s21, v229, 38
	v_readlane_b32 s22, v229, 39
	v_readlane_b32 s23, v229, 40
	v_readlane_b32 s26, v229, 43
	v_readlane_b32 s27, v229, 44
	ds_read_b128 v[234:237], v128
	ds_read_b128 v[238:241], v128 offset:32
	ds_read_b128 v[242:245], v128 offset:64
	ds_read_b128 v[246:249], v128 offset:96
	s_add_i32 s55, s30, s54
	s_cmp_eq_u32 s30, 7
	s_cbranch_scc1 .LBB0_433
	s_branch .LBB0_432

; DI f32x16 mfma32(bf16x8 a, bf16x8 b, f32x16 c) { return __builtin_amdgcn_mfma_f32_32x32x16_bf16(a, b, c, 0, 0, 0); }
; DI void nsa_cmp_unit(const Params& p, int u, char* smem) {
;     ...
;     l += __shfl_xor(l, 32);
;     const float inv = l > 0.f ? 1.f / l : 0.f;
;     f32x16 o[2]; zero_o(o);
; #pragma unroll 1
;     for (int T = 0; T < ntile; ++T) {
;       f32x16 s;
; #pragma unroll
;       for (int i = 0; i < 16; ++i) s[i] = 0.f;
; #pragma unroll
;       for (int ks = 0; ks < 4; ++ks) s = mfma32(*(const bf16x8*)(Kc + (32 * T + r) * LSTR + 16 * ks + 8 * h), qf[ks], s);
.LBB0_436:
	ds_bpermute_b32 v34, v126, v0
	s_and_b64 vcc, exec, s[6:7]
	s_cbranch_vccnz .LBB0_447
	ds_read_b128 v[234:237], v128
	ds_read_b128 v[238:241], v128 offset:32
	ds_read_b128 v[242:245], v128 offset:64
	ds_read_b128 v[246:249], v128 offset:96
	s_waitcnt lgkmcnt(4)
	v_add_f32_e32 v0, v0, v34
	v_div_scale_f32 v35, s[6:7], v0, v0, 1.0
	v_rcp_f32_e32 v36, v35
	v_mov_b32_e32 v34, 0
	s_mov_b32 s33, 0
	v_mov_b32_e32 v141, v128
	v_fma_f32 v37, -v35, v36, 1.0
	v_fmac_f32_e32 v36, v37, v36
	v_div_scale_f32 v37, vcc, 1.0, v0, 1.0
	v_mul_f32_e32 v38, v37, v36
	v_fma_f32 v39, -v35, v38, v37
	v_fmac_f32_e32 v38, v39, v36
	v_fma_f32 v35, -v35, v38, v37
	v_div_fmas_f32 v35, v35, v36, v38
	v_div_fixup_f32 v35, v35, v0, 1.0
	v_cmp_lt_f32_e32 vcc, 0, v0
	v_mov_b32_e32 v0, v127
	v_mov_b32_e32 v142, v130
	v_cndmask_b32_e32 v122, 0, v35, vcc
	v_mov_b32_e32 v123, v122
	v_mov_b32_e32 v35, v34
	v_mov_b32_e32 v36, v34
	v_mov_b32_e32 v37, v34
	v_mov_b32_e32 v38, v34
	v_mov_b32_e32 v39, v34
	v_mov_b32_e32 v40, v34
	v_mov_b32_e32 v41, v34
	v_mov_b32_e32 v42, v34
	v_mov_b32_e32 v43, v34
	v_mov_b32_e32 v44, v34
	v_mov_b32_e32 v45, v34
	v_mov_b32_e32 v46, v34
	v_mov_b32_e32 v47, v34
	v_mov_b32_e32 v48, v34
	v_mov_b32_e32 v49, v34
	v_mov_b32_e32 v50, v34
	v_mov_b32_e32 v51, v34
	v_mov_b32_e32 v52, v34
	v_mov_b32_e32 v53, v34
	v_mov_b32_e32 v54, v34
	v_mov_b32_e32 v55, v34
	v_mov_b32_e32 v56, v34
	v_mov_b32_e32 v57, v34
	v_mov_b32_e32 v58, v34
	v_mov_b32_e32 v59, v34
	v_mov_b32_e32 v60, v34
	v_mov_b32_e32 v61, v34
	v_mov_b32_e32 v62, v34
	v_mov_b32_e32 v63, v34
	v_mov_b32_e32 v64, v34
	v_mov_b32_e32 v65, v34
	s_branch .LBB0_439

; DI int crow(int i, int h) { return (i & 3) + 8 * (i >> 2) + 4 * h; }
; DI void nsa_cmp_unit(const Params& p, int u, char* smem) {
;     ...
;     store_plain(o, 1.f, p.Q + (size_t)NTOK * 1024 + tok * 1024 + head * 64);
;   }
;   __syncthreads();
;   float* imp_s = (float*)smem;
; #pragma unroll
;   for (int jt = 0; jt < 2; ++jt)
; #pragma unroll
;     for (int i = 0; i < 16; ++i) imp_s[(32 * w + r) * 65 + 32 * jt + crow(i, h)] = imp[jt][i];
;   __syncthreads();
;   if (tid < 128) {
;     const int t = 128 * qb + tid, cur = t >> 6;
;     ull mask = 1ull | (1ull << cur);
;     if (cur >= 2) {
;       const int need = (cur - 1) < 6 ? (cur - 1) : 6;
.LBB0_448:
	ds_read_b128 v[234:237], v128
	ds_read_b128 v[238:241], v128 offset:32
	ds_read_b128 v[242:245], v128 offset:64
	ds_read_b128 v[246:249], v128 offset:96
	s_lshl_b32 s58, s55, 7
	v_lshl_add_u64 v[66:67], v[118:119], 0, s[58:59]
	v_cvt_pk_bf16_f32 v34, v34, v35
	v_cvt_pk_bf16_f32 v35, v36, v37
	global_store_dwordx2 v[66:67], v[34:35], off
	v_cvt_pk_bf16_f32 v34, v38, v39
	v_cvt_pk_bf16_f32 v35, v40, v41
	global_store_dwordx2 v[66:67], v[34:35], off offset:16
	v_cvt_pk_bf16_f32 v34, v42, v43
	v_cvt_pk_bf16_f32 v35, v44, v45
	global_store_dwordx2 v[66:67], v[34:35], off offset:32
	v_cvt_pk_bf16_f32 v34, v46, v47
	v_cvt_pk_bf16_f32 v35, v48, v49
	global_store_dwordx2 v[66:67], v[34:35], off offset:48
	v_cvt_pk_bf16_f32 v34, v50, v51
	v_cvt_pk_bf16_f32 v35, v52, v53
	global_store_dwordx2 v[66:67], v[34:35], off offset:64
	v_cvt_pk_bf16_f32 v34, v54, v55
	v_cvt_pk_bf16_f32 v35, v56, v57
	s_add_i32 s30, s30, 1
	global_store_dwordx2 v[66:67], v[34:35], off offset:80
	v_cvt_pk_bf16_f32 v34, v58, v59
	v_cvt_pk_bf16_f32 v35, v60, v61
	global_store_dwordx2 v[66:67], v[34:35], off offset:96
	v_cvt_pk_bf16_f32 v34, v62, v63
	v_cvt_pk_bf16_f32 v35, v64, v65
	s_cmp_eq_u32 s30, 8
	global_store_dwordx2 v[66:67], v[34:35], off offset:112
	s_cbranch_scc0 .LBB0_431
	v_or_b32_e32 v0, s29, v124
	s_movk_i32 s4, 0x104
	v_mul_lo_u32 v0, v0, s4
	s_movk_i32 s4, 0x80
	v_add3_u32 v0, 0, v0, v125
	v_cmp_gt_i32_e32 vcc, s4, v114
	s_barrier
	ds_write2_b32 v0, v18, v19 offset1:1
	ds_write2_b32 v0, v20, v21 offset0:2 offset1:3
	ds_write2_b32 v0, v22, v23 offset0:8 offset1:9
	ds_write2_b32 v0, v24, v25 offset0:10 offset1:11
	ds_write2_b32 v0, v26, v27 offset0:16 offset1:17
	ds_write2_b32 v0, v28, v29 offset0:18 offset1:19
	ds_write2_b32 v0, v30, v31 offset0:24 offset1:25
	ds_write2_b32 v0, v32, v33 offset0:26 offset1:27
	ds_write2_b32 v0, v2, v3 offset0:32 offset1:33
	ds_write2_b32 v0, v4, v5 offset0:34 offset1:35
	ds_write2_b32 v0, v6, v7 offset0:40 offset1:41
	ds_write2_b32 v0, v8, v9 offset0:42 offset1:43
	ds_write2_b32 v0, v10, v11 offset0:48 offset1:49
	ds_write2_b32 v0, v12, v13 offset0:50 offset1:51
	ds_write2_b32 v0, v14, v15 offset0:56 offset1:57
	ds_write2_b32 v0, v16, v17 offset0:58 offset1:59
	s_waitcnt lgkmcnt(0)
	s_barrier
	s_and_saveexec_b64 s[4:5], vcc
	s_cbranch_execz .LBB0_429
	v_add_u32_e32 v2, s28, v114
	v_ashrrev_i32_e32 v3, 6, v2
	v_lshlrev_b64 v[4:5], v3, 1
	v_or_b32_e32 v4, 1, v4
	v_cmp_lt_i32_e32 vcc, 1, v3
	s_and_saveexec_b64 s[8:9], vcc
	s_cbranch_execz .LBB0_428
	s_movk_i32 s6, 0x104
	v_min_u32_e32 v0, 7, v3
	v_mul_lo_u32 v7, v114, s6
	v_add_u32_e32 v6, -2, v0
	v_add3_u32 v7, 0, 4, v7
	v_readfirstlane_b32 s28, v3
	s_nop 3
	s_cmp_lt_u32 s28, 12
	s_cbranch_scc1 .Lsel_small
; DI void nsa_cmp_unit(const Params& p, int u, char* smem) {
;     ...
;     if (cur >= 2) {
;       const int need = (cur - 1) < 6 ? (cur - 1) : 6;
;       for (int k = 0; k < need; ++k) {
;         int best = 1; float bv = -1.f;
;         for (int jj = 1; jj < cur; ++jj) {
;           const float v = imp_s[tid * 65 + jj];
;           if (!((mask >> jj) & 1ull) && v > bv) { bv = v; best = jj; }
;         }
;         mask |= 1ull << best;
;       }
	ds_read_b32 v34, v7
	ds_read_b32 v35, v7 offset:4
	ds_read_b32 v36, v7 offset:8
	ds_read_b32 v37, v7 offset:12
	ds_read_b32 v38, v7 offset:16
	ds_read_b32 v39, v7 offset:20
	ds_read_b32 v40, v7 offset:24
	ds_read_b32 v41, v7 offset:28
	ds_read_b32 v42, v7 offset:32
	ds_read_b32 v43, v7 offset:36
	ds_read_b32 v44, v7 offset:40
	ds_read_b32 v45, v7 offset:44
	ds_read_b32 v46, v7 offset:48
	ds_read_b32 v47, v7 offset:52
	s_waitcnt lgkmcnt(0)
	ds_read_b32 v48, v7 offset:56
	ds_read_b32 v49, v7 offset:60
	ds_read_b32 v50, v7 offset:64
	ds_read_b32 v51, v7 offset:68
	ds_read_b32 v52, v7 offset:72
	ds_read_b32 v53, v7 offset:76
	ds_read_b32 v54, v7 offset:80
	ds_read_b32 v55, v7 offset:84
	ds_read_b32 v56, v7 offset:88
	ds_read_b32 v57, v7 offset:92
	ds_read_b32 v58, v7 offset:96
	ds_read_b32 v59, v7 offset:100
	ds_read_b32 v60, v7 offset:104
	ds_read_b32 v61, v7 offset:108
	s_waitcnt lgkmcnt(0)
	ds_read_b32 v62, v7 offset:112
	ds_read_b32 v63, v7 offset:116
	ds_read_b32 v64, v7 offset:120
	ds_read_b32 v65, v7 offset:124
	ds_read_b32 v66, v7 offset:128
	ds_read_b32 v67, v7 offset:132
	ds_read_b32 v68, v7 offset:136
	ds_read_b32 v69, v7 offset:140
	ds_read_b32 v70, v7 offset:144
	ds_read_b32 v71, v7 offset:148
	ds_read_b32 v72, v7 offset:152
	ds_read_b32 v73, v7 offset:156
	ds_read_b32 v74, v7 offset:160
	ds_read_b32 v75, v7 offset:164
	s_waitcnt lgkmcnt(0)
	ds_read_b32 v76, v7 offset:168
	ds_read_b32 v77, v7 offset:172
	ds_read_b32 v78, v7 offset:176
	ds_read_b32 v79, v7 offset:180
	ds_read_b32 v80, v7 offset:184
	ds_read_b32 v81, v7 offset:188
	ds_read_b32 v82, v7 offset:192
	ds_read_b32 v83, v7 offset:196
	ds_read_b32 v84, v7 offset:200
	ds_read_b32 v85, v7 offset:204
	ds_read_b32 v86, v7 offset:208
	ds_read_b32 v87, v7 offset:212
	ds_read_b32 v88, v7 offset:216
	ds_read_b32 v89, v7 offset:220
	s_waitcnt lgkmcnt(0)
	ds_read_b32 v90, v7 offset:224
	ds_read_b32 v91, v7 offset:228
	ds_read_b32 v92, v7 offset:232
	ds_read_b32 v93, v7 offset:236
	ds_read_b32 v94, v7 offset:240
	ds_read_b32 v95, v7 offset:244
	s_add_i32 s100, s28, -1
	s_min_u32 s100, s100, 6
	v_mov_b32_e32 v12, -1.0
	s_waitcnt lgkmcnt(0)
	v_cmp_gt_u32_e64 s[6:7], v3, 1
	v_cmp_gt_u32_e64 s[10:11], v3, 2
	v_cmp_gt_u32_e64 vcc, v3, 3
	v_cndmask_b32_e64 v34, v12, v34, s[6:7]
	v_cmp_gt_u32_e64 s[6:7], v3, 4
	v_cndmask_b32_e64 v35, v12, v35, s[10:11]
	v_cmp_gt_u32_e64 s[10:11], v3, 5
	v_cndmask_b32_e64 v36, v12, v36, vcc
	v_cmp_gt_u32_e64 vcc, v3, 6
	v_cndmask_b32_e64 v37, v12, v37, s[6:7]
	v_cmp_gt_u32_e64 s[6:7], v3, 7
	v_cndmask_b32_e64 v38, v12, v38, s[10:11]
	v_cmp_gt_u32_e64 s[10:11], v3, 8
	v_cndmask_b32_e64 v39, v12, v39, vcc
	v_cmp_gt_u32_e64 vcc, v3, 9
	v_cndmask_b32_e64 v40, v12, v40, s[6:7]
	v_cmp_gt_u32_e64 s[6:7], v3, 10
	v_cndmask_b32_e64 v41, v12, v41, s[10:11]
	v_cmp_gt_u32_e64 s[10:11], v3, 11
	v_cndmask_b32_e64 v42, v12, v42, vcc
	v_cmp_gt_u32_e64 vcc, v3, 12
	v_cndmask_b32_e64 v43, v12, v43, s[6:7]
	v_cmp_gt_u32_e64 s[6:7], v3, 13
	v_cndmask_b32_e64 v44, v12, v44, s[10:11]
	v_cmp_gt_u32_e64 s[10:11], v3, 14
	v_cndmask_b32_e64 v45, v12, v45, vcc
	v_cmp_gt_u32_e64 vcc, v3, 15
	v_cndmask_b32_e64 v46, v12, v46, s[6:7]
	v_cmp_gt_u32_e64 s[6:7], v3, 16
	v_cndmask_b32_e64 v47, v12, v47, s[10:11]
	v_cmp_gt_u32_e64 s[10:11], v3, 17
	v_cndmask_b32_e64 v48, v12, v48, vcc
	v_cmp_gt_u32_e64 vcc, v3, 18
	v_cndmask_b32_e64 v49, v12, v49, s[6:7]
	v_cmp_gt_u32_e64 s[6:7], v3, 19
	v_cndmask_b32_e64 v50, v12, v50, s[10:11]
	v_cmp_gt_u32_e64 s[10:11], v3, 20
	v_cndmask_b32_e64 v51, v12, v51, vcc
	v_cmp_gt_u32_e64 vcc, v3, 21
	v_cndmask_b32_e64 v52, v12, v52, s[6:7]
	v_cmp_gt_u32_e64 s[6:7], v3, 22
	v_cndmask_b32_e64 v53, v12, v53, s[10:11]
	v_cmp_gt_u32_e64 s[10:11], v3, 23
	v_cndmask_b32_e64 v54, v12, v54, vcc
	v_cmp_gt_u32_e64 vcc, v3, 24
	v_cndmask_b32_e64 v55, v12, v55, s[6:7]
	v_cmp_gt_u32_e64 s[6:7], v3, 25
	v_cndmask_b32_e64 v56, v12, v56, s[10:11]
	v_cmp_gt_u32_e64 s[10:11], v3, 26
	v_cndmask_b32_e64 v57, v12, v57, vcc
	v_cmp_gt_u32_e64 vcc, v3, 27
	v_cndmask_b32_e64 v58, v12, v58, s[6:7]
	v_cmp_gt_u32_e64 s[6:7], v3, 28
	v_cndmask_b32_e64 v59, v12, v59, s[10:11]
	v_cmp_gt_u32_e64 s[10:11], v3, 29
	v_cndmask_b32_e64 v60, v12, v60, vcc
	v_cmp_gt_u32_e64 vcc, v3, 30
	v_cndmask_b32_e64 v61, v12, v61, s[6:7]
	v_cmp_gt_u32_e64 s[6:7], v3, 31
	v_cndmask_b32_e64 v62, v12, v62, s[10:11]
	v_cmp_gt_u32_e64 s[10:11], v3, 32
	v_cndmask_b32_e64 v63, v12, v63, vcc
	v_cmp_gt_u32_e64 vcc, v3, 33
	v_cndmask_b32_e64 v64, v12, v64, s[6:7]
	v_cmp_gt_u32_e64 s[6:7], v3, 34
	v_cndmask_b32_e64 v65, v12, v65, s[10:11]
	v_cmp_gt_u32_e64 s[10:11], v3, 35
	v_cndmask_b32_e64 v66, v12, v66, vcc
	v_cmp_gt_u32_e64 vcc, v3, 36
	v_cndmask_b32_e64 v67, v12, v67, s[6:7]
	v_cmp_gt_u32_e64 s[6:7], v3, 37
	v_cndmask_b32_e64 v68, v12, v68, s[10:11]
	v_cmp_gt_u32_e64 s[10:11], v3, 38
	v_cndmask_b32_e64 v69, v12, v69, vcc
	v_cmp_gt_u32_e64 vcc, v3, 39
	v_cndmask_b32_e64 v70, v12, v70, s[6:7]
	v_cmp_gt_u32_e64 s[6:7], v3, 40
	v_cndmask_b32_e64 v71, v12, v71, s[10:11]
	v_cmp_gt_u32_e64 s[10:11], v3, 41
	v_cndmask_b32_e64 v72, v12, v72, vcc
	v_cmp_gt_u32_e64 vcc, v3, 42
	v_cndmask_b32_e64 v73, v12, v73, s[6:7]
	v_cmp_gt_u32_e64 s[6:7], v3, 43
	v_cndmask_b32_e64 v74, v12, v74, s[10:11]
	v_cmp_gt_u32_e64 s[10:11], v3, 44
	v_cndmask_b32_e64 v75, v12, v75, vcc
	v_cmp_gt_u32_e64 vcc, v3, 45
	v_cndmask_b32_e64 v76, v12, v76, s[6:7]
	v_cmp_gt_u32_e64 s[6:7], v3, 46
	v_cndmask_b32_e64 v77, v12, v77, s[10:11]
	v_cmp_gt_u32_e64 s[10:11], v3, 47
	v_cndmask_b32_e64 v78, v12, v78, vcc
	v_cmp_gt_u32_e64 vcc, v3, 48
	v_cndmask_b32_e64 v79, v12, v79, s[6:7]
	v_cmp_gt_u32_e64 s[6:7], v3, 49
	v_cndmask_b32_e64 v80, v12, v80, s[10:11]
	v_cmp_gt_u32_e64 s[10:11], v3, 50
	v_cndmask_b32_e64 v81, v12, v81, vcc
	v_cmp_gt_u32_e64 vcc, v3, 51
	v_cndmask_b32_e64 v82, v12, v82, s[6:7]
	v_cmp_gt_u32_e64 s[6:7], v3, 52
	v_cndmask_b32_e64 v83, v12, v83, s[10:11]
	v_cmp_gt_u32_e64 s[10:11], v3, 53
	v_cndmask_b32_e64 v84, v12, v84, vcc
	v_cmp_gt_u32_e64 vcc, v3, 54
	v_cndmask_b32_e64 v85, v12, v85, s[6:7]
	v_cmp_gt_u32_e64 s[6:7], v3, 55
	v_cndmask_b32_e64 v86, v12, v86, s[10:11]
	v_cmp_gt_u32_e64 s[10:11], v3, 56
	v_cndmask_b32_e64 v87, v12, v87, vcc
	v_cmp_gt_u32_e64 vcc, v3, 57
	v_cndmask_b32_e64 v88, v12, v88, s[6:7]
	v_cmp_gt_u32_e64 s[6:7], v3, 58
	v_cndmask_b32_e64 v89, v12, v89, s[10:11]
	v_cmp_gt_u32_e64 s[10:11], v3, 59
	v_cndmask_b32_e64 v90, v12, v90, vcc
	v_cmp_gt_u32_e64 vcc, v3, 60
	v_cndmask_b32_e64 v91, v12, v91, s[6:7]
	v_cmp_gt_u32_e64 s[6:7], v3, 61
	v_cndmask_b32_e64 v92, v12, v92, s[10:11]
	v_cmp_gt_u32_e64 s[10:11], v3, 62
	v_cndmask_b32_e64 v93, v12, v93, vcc
	s_nop 1
	v_cndmask_b32_e64 v94, v12, v94, s[6:7]
	v_cndmask_b32_e64 v95, v12, v95, s[10:11]
